# v38 + attention epilogue RMS-norm reduction: xor-2 shuffles via DPP quad_perm[2,3,0,1] instead of ds_bpermute
# speedup vs baseline: 1.0144x; 1.0144x over previous
; __device__ __forceinline__ int crow(int r, int hi) { return (r & 3) + 8 * (r >> 2) + 4 * hi; }
; __device__ __forceinline__ bool fox_block(const BlockRef& cur, BlockRef& nxt, unsigned* ctr, const unsigned* nrm, bf16_t* PROJ, bf16_t* MIX, char* lds, Seam& S, const float* __restrict__ CF, const float* __restrict__ fnorm) {
;     ...
;     if (hi == 0) li_l[r32] = l_reg; asm volatile("s_waitcnt lgkmcnt(0)" ::: "memory");
;     float rs[16];
; #pragma unroll
;     for (int r = 0; r < 16; ++r) { const float rl = __builtin_amdgcn_rcpf(li_l[crow(r, hi)]); float a = 0.f;
; #pragma unroll
;         for (int d0 = 0; d0 < 4; ++d0) { const float v = o[d0][r] * rl; o[d0][r] = v; a += v * v; }
;         a += __shfl_xor(a, 1); a += __shfl_xor(a, 2); a += __shfl_xor(a, 4); a += __shfl_xor(a, 8); a += __shfl_xor(a, 16);
;         rs[r] = rsqrtf(a * (1.f / 128.f) + RMS_EPS); }
.LBB0_822:
	s_ashr_i32 s73, s72, 31
	s_waitcnt vmcnt(8)
	s_waitcnt vmcnt(0) lgkmcnt(0)
	ds_write_b128 v213, v[102:105] offset:32768
	ds_write_b128 v213, v[110:113] offset:40960
	v_cmp_gt_u32_e32 vcc, 32, v214
	s_and_saveexec_b64 s[10:11], vcc
	ds_write_b32 v215, v114
	s_or_b64 exec, exec, s[10:11]
	v_and_b32_e32 v67, 64, v207
	v_xor_b32_e32 v66, 1, v207
	v_add_u32_e32 v67, 64, v67
	v_cmp_lt_i32_e32 vcc, v66, v67
	s_waitcnt lgkmcnt(0)
	v_mov_b32_e32 v74, v50
	v_mov_b32_e32 v75, v34
	v_cndmask_b32_e32 v66, v207, v66, vcc
	v_lshlrev_b32_e32 v116, 2, v66
	v_xor_b32_e32 v66, 2, v207
	v_cmp_lt_i32_e32 vcc, v66, v67
	v_mov_b32_e32 v34, v51
	v_lshl_or_b32 v196, s22, 7, v211
	v_cndmask_b32_e32 v66, v207, v66, vcc
	v_lshlrev_b32_e32 v118, 2, v66
	v_xor_b32_e32 v66, 4, v207
	v_cmp_lt_i32_e32 vcc, v66, v67
	s_nop 1
	v_cndmask_b32_e32 v66, v207, v66, vcc
	v_lshlrev_b32_e32 v119, 2, v66
	v_xor_b32_e32 v66, 8, v207
	v_cmp_lt_i32_e32 vcc, v66, v67
	s_nop 1
	v_cndmask_b32_e32 v66, v207, v66, vcc
	v_lshlrev_b32_e32 v120, 2, v66
	v_xor_b32_e32 v66, 16, v207
	v_cmp_lt_i32_e32 vcc, v66, v67
	s_nop 1
	v_cndmask_b32_e32 v66, v207, v66, vcc
	v_lshlrev_b32_e32 v121, 2, v66
	ds_read_b128 v[70:73], v212
	ds_read_b128 v[66:69], v212 offset:32
	s_waitcnt lgkmcnt(0)
	v_rcp_f32_e32 v70, v70
	s_nop 0
	v_pk_mul_f32 v[86:87], v[74:75], v[70:71] op_sel_hi:[1,0]
	v_mov_b32_e32 v74, v2
	v_rcp_f32_e32 v2, v71
	v_mov_b32_e32 v75, v18
	v_mov_b32_e32 v18, v3
	v_pk_mul_f32 v[76:77], v[86:87], v[86:87]
	v_pk_mul_f32 v[80:81], v[34:35], v[2:3] op_sel_hi:[1,0]
	v_pk_mul_f32 v[84:85], v[74:75], v[70:71] op_sel_hi:[1,0]
	v_pk_mul_f32 v[34:35], v[80:81], v[80:81]
	v_pk_mul_f32 v[74:75], v[18:19], v[2:3] op_sel_hi:[1,0]
	v_pk_mul_f32 v[78:79], v[84:85], v[84:85]
	v_pk_mul_f32 v[2:3], v[74:75], v[74:75]
	v_mov_b32_e32 v18, v34
	v_mov_b32_e32 v19, v76
	v_mov_b32_e32 v76, v35
	v_pk_add_f32 v[18:19], v[18:19], v[76:77]
	v_mov_b32_e32 v34, v3
	v_mov_b32_e32 v35, v79
	v_pk_add_f32 v[18:19], v[34:35], v[18:19]
	v_mov_b32_e32 v3, v78
	v_pk_add_f32 v[2:3], v[2:3], v[18:19]
	s_nop 1
	v_mov_b32_dpp v19, v3 quad_perm:[1,0,3,2] row_mask:0xf bank_mask:0xf
	s_nop 1
	v_mov_b32_dpp v18, v2 quad_perm:[1,0,3,2] row_mask:0xf bank_mask:0xf
	v_mov_b32_e32 v34, v4
	v_rcp_f32_e32 v4, v73
	v_mov_b32_e32 v35, v20
	v_mov_b32_e32 v20, v5
	s_waitcnt lgkmcnt(0)
	v_pk_add_f32 v[2:3], v[2:3], v[18:19]
	s_nop 1
	v_mov_b32_dpp v19, v3 quad_perm:[2,3,0,1] row_mask:0xf bank_mask:0xf
	s_nop 1
	v_mov_b32_dpp v18, v2 quad_perm:[2,3,0,1] row_mask:0xf bank_mask:0xf
	s_waitcnt lgkmcnt(0)
	v_pk_add_f32 v[2:3], v[2:3], v[18:19]
	ds_bpermute_b32 v19, v119, v3
	ds_bpermute_b32 v18, v119, v2
	s_waitcnt lgkmcnt(0)
	v_pk_add_f32 v[2:3], v[2:3], v[18:19]
	ds_bpermute_b32 v19, v120, v3
	ds_bpermute_b32 v18, v120, v2
	s_waitcnt lgkmcnt(0)
	v_pk_add_f32 v[2:3], v[2:3], v[18:19]
	ds_bpermute_b32 v19, v121, v3
	ds_bpermute_b32 v18, v121, v2
	s_waitcnt lgkmcnt(0)
	v_pk_add_f32 v[2:3], v[2:3], v[18:19]
	s_nop 0
	v_pk_fma_f32 v[94:95], v[2:3], s[48:49], v[198:199] op_sel_hi:[1,0,0]
	v_mov_b32_e32 v18, v52
	v_mul_f32_e32 v2, 0x4b800000, v95
	v_cmp_gt_f32_e64 s[10:11], s44, v95
	v_mov_b32_e32 v19, v36
	v_mov_b32_e32 v36, v53
	v_cndmask_b32_e64 v2, v95, v2, s[10:11]
	v_rsq_f32_e32 v2, v2
	v_pk_mul_f32 v[78:79], v[36:37], v[4:5] op_sel_hi:[1,0]
	v_cmp_gt_f32_e32 vcc, s44, v94
	v_mul_f32_e32 v3, 0x45800000, v2
	v_cndmask_b32_e64 v117, v2, v3, s[10:11]
	v_rcp_f32_e32 v2, v72
	v_pk_mul_f32 v[72:73], v[20:21], v[4:5] op_sel_hi:[1,0]
	s_lshl_b64 s[10:11], s[72:73], 12
	v_pk_mul_f32 v[4:5], v[72:73], v[72:73]
	v_pk_mul_f32 v[88:89], v[18:19], v[2:3] op_sel_hi:[1,0]
	v_pk_mul_f32 v[82:83], v[34:35], v[2:3] op_sel_hi:[1,0]
	v_pk_mul_f32 v[18:19], v[88:89], v[88:89]
	v_pk_mul_f32 v[34:35], v[78:79], v[78:79]
	v_pk_mul_f32 v[2:3], v[82:83], v[82:83]
	v_mov_b32_e32 v20, v34
	v_mov_b32_e32 v21, v18
	v_mov_b32_e32 v18, v35
	v_pk_add_f32 v[18:19], v[20:21], v[18:19]
	v_mov_b32_e32 v20, v5
	v_mov_b32_e32 v21, v3
	v_pk_add_f32 v[18:19], v[20:21], v[18:19]
	v_mov_b32_e32 v5, v2
	v_pk_add_f32 v[2:3], v[4:5], v[18:19]
	s_nop 1
	v_mov_b32_dpp v5, v3 quad_perm:[1,0,3,2] row_mask:0xf bank_mask:0xf
	s_nop 1
	v_mov_b32_dpp v4, v2 quad_perm:[1,0,3,2] row_mask:0xf bank_mask:0xf
	v_mov_b32_e32 v18, v6
	v_rcp_f32_e32 v6, v67
	v_mov_b32_e32 v19, v22
	v_mov_b32_e32 v22, v7
	s_waitcnt lgkmcnt(0)
	v_pk_add_f32 v[2:3], v[2:3], v[4:5]
	s_nop 1
	v_mov_b32_dpp v5, v3 quad_perm:[2,3,0,1] row_mask:0xf bank_mask:0xf
	s_nop 1
	v_mov_b32_dpp v4, v2 quad_perm:[2,3,0,1] row_mask:0xf bank_mask:0xf
	v_pk_mul_f32 v[50:51], v[22:23], v[6:7] op_sel_hi:[1,0]
	s_add_u32 s12, s70, s10
	s_addc_u32 s13, s71, s11
	s_waitcnt lgkmcnt(0)
	v_pk_add_f32 v[2:3], v[2:3], v[4:5]
	ds_bpermute_b32 v5, v119, v3
	ds_bpermute_b32 v4, v119, v2
	s_waitcnt lgkmcnt(0)
	v_pk_add_f32 v[2:3], v[2:3], v[4:5]
	ds_bpermute_b32 v5, v120, v3
	ds_bpermute_b32 v4, v120, v2
	s_waitcnt lgkmcnt(0)
	v_pk_add_f32 v[96:97], v[2:3], v[4:5]
	v_rcp_f32_e32 v2, v66
	v_mov_b32_e32 v4, v54
	v_mov_b32_e32 v5, v38
	v_mov_b32_e32 v38, v55
	v_pk_mul_f32 v[76:77], v[4:5], v[2:3] op_sel_hi:[1,0]
	v_pk_mul_f32 v[54:55], v[38:39], v[6:7] op_sel_hi:[1,0]
	v_pk_mul_f32 v[4:5], v[76:77], v[76:77]
	v_pk_mul_f32 v[70:71], v[18:19], v[2:3] op_sel_hi:[1,0]
	v_pk_mul_f32 v[18:19], v[54:55], v[54:55]
	v_pk_mul_f32 v[2:3], v[70:71], v[70:71]
	v_pk_mul_f32 v[6:7], v[50:51], v[50:51]
	v_mov_b32_e32 v20, v18
	v_mov_b32_e32 v21, v4
	v_mov_b32_e32 v4, v19
	v_pk_add_f32 v[4:5], v[20:21], v[4:5]
	v_mov_b32_e32 v18, v7
	v_mov_b32_e32 v19, v3
	v_pk_add_f32 v[4:5], v[18:19], v[4:5]
	v_mov_b32_e32 v7, v2
	v_pk_add_f32 v[2:3], v[6:7], v[4:5]
	s_nop 1
	v_mov_b32_dpp v5, v3 quad_perm:[1,0,3,2] row_mask:0xf bank_mask:0xf
	s_nop 1
	v_mov_b32_dpp v4, v2 quad_perm:[1,0,3,2] row_mask:0xf bank_mask:0xf
	v_mov_b32_e32 v6, v8
	v_mov_b32_e32 v7, v24
	v_mov_b32_e32 v24, v9
	ds_bpermute_b32 v115, v121, v97
	s_waitcnt lgkmcnt(0)
; __device__ __forceinline__ int crow(int r, int hi) { return (r & 3) + 8 * (r >> 2) + 4 * hi; }
; __device__ __forceinline__ bool fox_block(const BlockRef& cur, BlockRef& nxt, unsigned* ctr, const unsigned* nrm, bf16_t* PROJ, bf16_t* MIX, char* lds, Seam& S, const float* __restrict__ CF, const float* __restrict__ fnorm) {
;     ...
;     for (int r = 0; r < 16; ++r) { const float rl = __builtin_amdgcn_rcpf(li_l[crow(r, hi)]); float a = 0.f;
; #pragma unroll
;         for (int d0 = 0; d0 < 4; ++d0) { const float v = o[d0][r] * rl; o[d0][r] = v; a += v * v; }
;         a += __shfl_xor(a, 1); a += __shfl_xor(a, 2); a += __shfl_xor(a, 4); a += __shfl_xor(a, 8); a += __shfl_xor(a, 16);
;         rs[r] = rsqrtf(a * (1.f / 128.f) + RMS_EPS); }
	v_pk_add_f32 v[2:3], v[2:3], v[4:5]
	s_nop 1
	v_mov_b32_dpp v5, v3 quad_perm:[2,3,0,1] row_mask:0xf bank_mask:0xf
	s_nop 1
	v_mov_b32_dpp v4, v2 quad_perm:[2,3,0,1] row_mask:0xf bank_mask:0xf
	ds_bpermute_b32 v114, v121, v96
	s_waitcnt lgkmcnt(0)
	v_pk_add_f32 v[2:3], v[2:3], v[4:5]
	ds_bpermute_b32 v5, v119, v3
	ds_bpermute_b32 v4, v119, v2
	s_waitcnt lgkmcnt(0)
	v_pk_add_f32 v[2:3], v[2:3], v[4:5]
	ds_bpermute_b32 v5, v120, v3
	ds_bpermute_b32 v4, v120, v2
	s_waitcnt lgkmcnt(0)
	v_pk_add_f32 v[90:91], v[2:3], v[4:5]
	v_rcp_f32_e32 v2, v68
	v_mov_b32_e32 v4, v56
	v_mov_b32_e32 v5, v40
	v_mov_b32_e32 v40, v57
	v_pk_mul_f32 v[52:53], v[6:7], v[2:3] op_sel_hi:[1,0]
	v_rcp_f32_e32 v6, v69
	v_pk_mul_f32 v[66:67], v[4:5], v[2:3] op_sel_hi:[1,0]
	v_pk_mul_f32 v[2:3], v[52:53], v[52:53]
	v_pk_mul_f32 v[4:5], v[66:67], v[66:67]
	v_pk_mul_f32 v[40:41], v[40:41], v[6:7] op_sel_hi:[1,0]
	v_pk_mul_f32 v[36:37], v[24:25], v[6:7] op_sel_hi:[1,0]
	v_pk_mul_f32 v[18:19], v[40:41], v[40:41]
	v_pk_mul_f32 v[6:7], v[36:37], v[36:37]
	v_mov_b32_e32 v8, v18
	v_mov_b32_e32 v9, v4
	v_mov_b32_e32 v4, v19
	v_pk_add_f32 v[4:5], v[8:9], v[4:5]
	v_mov_b32_e32 v8, v7
	v_mov_b32_e32 v9, v3
	v_pk_add_f32 v[4:5], v[8:9], v[4:5]
	v_mov_b32_e32 v7, v2
	v_pk_add_f32 v[2:3], v[6:7], v[4:5]
	s_nop 1
	v_mov_b32_dpp v5, v3 quad_perm:[1,0,3,2] row_mask:0xf bank_mask:0xf
	s_nop 1
	v_mov_b32_dpp v4, v2 quad_perm:[1,0,3,2] row_mask:0xf bank_mask:0xf
	v_mov_b32_e32 v6, v58
	v_mov_b32_e32 v7, v42
	v_mov_b32_e32 v8, v10
	v_mov_b32_e32 v9, v26
	s_waitcnt lgkmcnt(0)
	v_pk_add_f32 v[2:3], v[2:3], v[4:5]
	s_nop 1
	v_mov_b32_dpp v5, v3 quad_perm:[2,3,0,1] row_mask:0xf bank_mask:0xf
	s_nop 1
	v_mov_b32_dpp v4, v2 quad_perm:[2,3,0,1] row_mask:0xf bank_mask:0xf
	v_mov_b32_e32 v42, v59
	v_mov_b32_e32 v26, v11
	ds_bpermute_b32 v93, v121, v91
	ds_bpermute_b32 v92, v121, v90
	s_waitcnt lgkmcnt(0)
	v_pk_add_f32 v[2:3], v[2:3], v[4:5]
	ds_bpermute_b32 v5, v119, v3
	ds_bpermute_b32 v4, v119, v2
	s_waitcnt lgkmcnt(0)
	v_pk_add_f32 v[2:3], v[2:3], v[4:5]
	ds_bpermute_b32 v5, v120, v3
	ds_bpermute_b32 v4, v120, v2
	s_waitcnt lgkmcnt(0)
	v_pk_add_f32 v[56:57], v[2:3], v[4:5]
	ds_read_b128 v[2:5], v212 offset:64
	ds_bpermute_b32 v69, v121, v57
	ds_bpermute_b32 v68, v121, v56
	s_waitcnt lgkmcnt(0)
	v_rcp_f32_e32 v2, v2
	s_nop 0
	v_pk_mul_f32 v[38:39], v[6:7], v[2:3] op_sel_hi:[1,0]
	v_pk_mul_f32 v[34:35], v[8:9], v[2:3] op_sel_hi:[1,0]
	v_rcp_f32_e32 v2, v3
	v_pk_mul_f32 v[6:7], v[38:39], v[38:39]
	v_pk_mul_f32 v[8:9], v[34:35], v[34:35]
	v_mov_b32_e32 v11, v6
	v_pk_mul_f32 v[24:25], v[42:43], v[2:3] op_sel_hi:[1,0]
	v_pk_mul_f32 v[20:21], v[26:27], v[2:3] op_sel_hi:[1,0]
	v_pk_mul_f32 v[18:19], v[24:25], v[24:25]
	v_pk_mul_f32 v[2:3], v[20:21], v[20:21]
	v_mov_b32_e32 v10, v18
	v_mov_b32_e32 v6, v19
	v_pk_add_f32 v[6:7], v[10:11], v[6:7]
	v_mov_b32_e32 v10, v3
	v_mov_b32_e32 v11, v9
	v_pk_add_f32 v[6:7], v[10:11], v[6:7]
	v_mov_b32_e32 v3, v8
	v_pk_add_f32 v[2:3], v[2:3], v[6:7]
	s_nop 1
	v_mov_b32_dpp v7, v3 quad_perm:[1,0,3,2] row_mask:0xf bank_mask:0xf
	s_nop 1
	v_mov_b32_dpp v6, v2 quad_perm:[1,0,3,2] row_mask:0xf bank_mask:0xf
	s_waitcnt lgkmcnt(0)
	v_pk_add_f32 v[2:3], v[2:3], v[6:7]
	s_nop 1
	v_mov_b32_dpp v7, v3 quad_perm:[2,3,0,1] row_mask:0xf bank_mask:0xf
	s_nop 1
	v_mov_b32_dpp v6, v2 quad_perm:[2,3,0,1] row_mask:0xf bank_mask:0xf
	s_waitcnt lgkmcnt(0)
	v_pk_add_f32 v[2:3], v[2:3], v[6:7]
	ds_bpermute_b32 v7, v119, v3
	ds_bpermute_b32 v6, v119, v2
	s_waitcnt lgkmcnt(0)
	v_pk_add_f32 v[2:3], v[2:3], v[6:7]
	ds_bpermute_b32 v7, v120, v3
	ds_bpermute_b32 v6, v120, v2
	s_waitcnt lgkmcnt(0)
	v_pk_add_f32 v[26:27], v[2:3], v[6:7]
	v_rcp_f32_e32 v2, v4
	v_rcp_f32_e32 v4, v5
	v_mov_b32_e32 v6, v60
	v_mov_b32_e32 v7, v44
	v_mov_b32_e32 v44, v61
	v_pk_mul_f32 v[18:19], v[6:7], v[2:3] op_sel_hi:[1,0]
	v_mov_b32_e32 v6, v12
	v_mov_b32_e32 v7, v28
	v_pk_mul_f32 v[8:9], v[44:45], v[4:5] op_sel_hi:[1,0]
	v_mov_b32_e32 v28, v13
	v_pk_mul_f32 v[22:23], v[18:19], v[18:19]
	v_pk_mul_f32 v[10:11], v[6:7], v[2:3] op_sel_hi:[1,0]
	v_pk_mul_f32 v[44:45], v[8:9], v[8:9]
	v_pk_mul_f32 v[6:7], v[28:29], v[4:5] op_sel_hi:[1,0]
	v_pk_mul_f32 v[2:3], v[10:11], v[10:11]
	v_pk_mul_f32 v[4:5], v[6:7], v[6:7]
	v_mov_b32_e32 v12, v44
	v_mov_b32_e32 v13, v22
	v_mov_b32_e32 v22, v45
	v_pk_add_f32 v[12:13], v[12:13], v[22:23]
	v_mov_b32_e32 v22, v5
	v_mov_b32_e32 v23, v3
	v_pk_add_f32 v[12:13], v[22:23], v[12:13]
	v_mov_b32_e32 v5, v2
	v_pk_add_f32 v[2:3], v[4:5], v[12:13]
	s_nop 1
	v_mov_b32_dpp v5, v3 quad_perm:[1,0,3,2] row_mask:0xf bank_mask:0xf
	s_nop 1
	v_mov_b32_dpp v4, v2 quad_perm:[1,0,3,2] row_mask:0xf bank_mask:0xf
	v_mov_b32_e32 v28, v62
	v_mov_b32_e32 v29, v46
	v_mov_b32_e32 v44, v14
	v_mov_b32_e32 v45, v30
	s_waitcnt lgkmcnt(0)
; __device__ __forceinline__ unsigned cvt_pk_bf16(float lo, float hi) { unsigned r; asm volatile("v_cvt_pk_bf16_f32 %0, %1, %2" : "=v"(r) : "v"(lo), "v"(hi)); return r; }
; __device__ __forceinline__ int crow(int r, int hi) { return (r & 3) + 8 * (r >> 2) + 4 * hi; }
; __device__ __forceinline__ bool fox_block(const BlockRef& cur, BlockRef& nxt, unsigned* ctr, const unsigned* nrm, bf16_t* PROJ, bf16_t* MIX, char* lds, Seam& S, const float* __restrict__ CF, const float* __restrict__ fnorm) {
;     ...
;     for (int r = 0; r < 16; ++r) { const float rl = __builtin_amdgcn_rcpf(li_l[crow(r, hi)]); float a = 0.f;
; #pragma unroll
;         for (int d0 = 0; d0 < 4; ++d0) { const float v = o[d0][r] * rl; o[d0][r] = v; a += v * v; }
;         a += __shfl_xor(a, 1); a += __shfl_xor(a, 2); a += __shfl_xor(a, 4); a += __shfl_xor(a, 8); a += __shfl_xor(a, 16);
;         rs[r] = rsqrtf(a * (1.f / 128.f) + RMS_EPS); }
;     float gn[4];
; #pragma unroll
;     for (int d0 = 0; d0 < 4; ++d0) gn[d0] = fnorm[cur.head * 128 + d0 * 32 + r32];
;     bf16_t* Ow = cur.O + (size_t)(wid * QBLK) * DM;
; #pragma unroll
;     for (int r = 0; r < 16; ++r) { const int orow = crow(r, hi);
; #pragma unroll
;         for (int d0 = 0; d0 < 4; ++d0) { const float v = o[d0][r] * rs[r] * gn[d0];
;             const float vn = __shfl_xor(v, 1);
;             if ((r32 & 1) == 0) *(unsigned*)(Ow + (size_t)orow * DM + d0 * 32 + r32) = cvt_pk_bf16(v, vn); } }
	v_pk_add_f32 v[2:3], v[2:3], v[4:5]
	s_nop 1
	v_mov_b32_dpp v5, v3 quad_perm:[2,3,0,1] row_mask:0xf bank_mask:0xf
	s_nop 1
	v_mov_b32_dpp v4, v2 quad_perm:[2,3,0,1] row_mask:0xf bank_mask:0xf
	v_mov_b32_e32 v46, v63
	v_mov_b32_e32 v30, v15
	ds_bpermute_b32 v43, v121, v27
	ds_bpermute_b32 v42, v121, v26
	s_waitcnt lgkmcnt(0)
	v_pk_add_f32 v[2:3], v[2:3], v[4:5]
	ds_bpermute_b32 v5, v119, v3
	ds_bpermute_b32 v4, v119, v2
	s_waitcnt lgkmcnt(0)
	v_pk_add_f32 v[2:3], v[2:3], v[4:5]
	ds_bpermute_b32 v5, v120, v3
	ds_bpermute_b32 v4, v120, v2
	s_waitcnt lgkmcnt(0)
	v_pk_add_f32 v[12:13], v[2:3], v[4:5]
	ds_read_b128 v[2:5], v212 offset:96
	ds_bpermute_b32 v23, v121, v13
	ds_bpermute_b32 v22, v121, v12
	s_waitcnt lgkmcnt(0)
	v_rcp_f32_e32 v2, v2
	s_nop 0
	v_pk_mul_f32 v[60:61], v[28:29], v[2:3] op_sel_hi:[1,0]
	v_pk_mul_f32 v[58:59], v[44:45], v[2:3] op_sel_hi:[1,0]
	v_rcp_f32_e32 v2, v3
	v_pk_mul_f32 v[28:29], v[60:61], v[60:61]
	v_pk_mul_f32 v[122:123], v[58:59], v[58:59]
	v_mov_b32_e32 v15, v28
	v_pk_mul_f32 v[44:45], v[46:47], v[2:3] op_sel_hi:[1,0]
	v_pk_mul_f32 v[30:31], v[30:31], v[2:3] op_sel_hi:[1,0]
	v_pk_mul_f32 v[46:47], v[44:45], v[44:45]
	v_pk_mul_f32 v[2:3], v[30:31], v[30:31]
	v_mov_b32_e32 v14, v46
	v_mov_b32_e32 v28, v47
	v_pk_add_f32 v[14:15], v[14:15], v[28:29]
	v_mov_b32_e32 v28, v3
	v_mov_b32_e32 v29, v123
	v_pk_add_f32 v[14:15], v[28:29], v[14:15]
	v_mov_b32_e32 v3, v122
	v_pk_add_f32 v[2:3], v[2:3], v[14:15]
	s_nop 1
	v_mov_b32_dpp v15, v3 quad_perm:[1,0,3,2] row_mask:0xf bank_mask:0xf
	s_nop 1
	v_mov_b32_dpp v14, v2 quad_perm:[1,0,3,2] row_mask:0xf bank_mask:0xf
	s_waitcnt lgkmcnt(0)
	v_pk_add_f32 v[2:3], v[2:3], v[14:15]
	s_nop 1
	v_mov_b32_dpp v15, v3 quad_perm:[2,3,0,1] row_mask:0xf bank_mask:0xf
	s_nop 1
	v_mov_b32_dpp v14, v2 quad_perm:[2,3,0,1] row_mask:0xf bank_mask:0xf
	s_waitcnt lgkmcnt(0)
	v_pk_add_f32 v[2:3], v[2:3], v[14:15]
	ds_bpermute_b32 v15, v119, v3
	ds_bpermute_b32 v14, v119, v2
	s_waitcnt lgkmcnt(0)
	v_pk_add_f32 v[2:3], v[2:3], v[14:15]
	ds_bpermute_b32 v15, v120, v3
	ds_bpermute_b32 v14, v120, v2
	s_waitcnt lgkmcnt(0)
	v_pk_add_f32 v[46:47], v[2:3], v[14:15]
	v_rcp_f32_e32 v2, v4
	v_mov_b32_e32 v14, v64
	v_mov_b32_e32 v15, v48
	v_mov_b32_e32 v48, v65
	v_pk_mul_f32 v[28:29], v[14:15], v[2:3] op_sel_hi:[1,0]
	v_mov_b32_e32 v14, v16
	v_mov_b32_e32 v15, v32
	v_pk_mul_f32 v[14:15], v[14:15], v[2:3] op_sel_hi:[1,0]
	v_rcp_f32_e32 v2, v5
	v_mov_b32_e32 v32, v17
	v_pk_mul_f32 v[122:123], v[28:29], v[28:29]
	v_pk_mul_f32 v[124:125], v[14:15], v[14:15]
	v_pk_mul_f32 v[4:5], v[48:49], v[2:3] op_sel_hi:[1,0]
	v_pk_mul_f32 v[2:3], v[32:33], v[2:3] op_sel_hi:[1,0]
	v_pk_mul_f32 v[48:49], v[4:5], v[4:5]
	v_pk_mul_f32 v[16:17], v[2:3], v[2:3]
	v_mov_b32_e32 v32, v48
	v_mov_b32_e32 v33, v122
	v_mov_b32_e32 v122, v49
	v_pk_add_f32 v[32:33], v[32:33], v[122:123]
	v_mov_b32_e32 v48, v17
	v_mov_b32_e32 v49, v125
	v_pk_add_f32 v[32:33], v[48:49], v[32:33]
	v_mov_b32_e32 v17, v124
	v_pk_add_f32 v[16:17], v[16:17], v[32:33]
	s_nop 1
	v_mov_b32_dpp v33, v17 quad_perm:[1,0,3,2] row_mask:0xf bank_mask:0xf
	s_nop 1
	v_mov_b32_dpp v32, v16 quad_perm:[1,0,3,2] row_mask:0xf bank_mask:0xf
	v_lshl_add_u64 v[48:49], v[196:197], 2, s[18:19]
	v_mul_f32_e32 v64, v86, v117
	ds_bpermute_b32 v63, v121, v47
	ds_bpermute_b32 v62, v121, v46
	s_waitcnt lgkmcnt(0)
	v_pk_add_f32 v[16:17], v[16:17], v[32:33]
	s_nop 1
	v_mov_b32_dpp v33, v17 quad_perm:[2,3,0,1] row_mask:0xf bank_mask:0xf
	s_nop 1
	v_mov_b32_dpp v32, v16 quad_perm:[2,3,0,1] row_mask:0xf bank_mask:0xf
	v_lshlrev_b32_e32 v196, 1, v211
	s_waitcnt lgkmcnt(0)
	v_pk_add_f32 v[16:17], v[16:17], v[32:33]
	ds_bpermute_b32 v33, v119, v17
	ds_bpermute_b32 v32, v119, v16
	s_waitcnt lgkmcnt(0)
	v_pk_add_f32 v[16:17], v[16:17], v[32:33]
	ds_bpermute_b32 v33, v120, v17
	ds_bpermute_b32 v32, v120, v16
	flat_load_dword v120, v[48:49]
	flat_load_dword v119, v[48:49] offset:128
	flat_load_dword v118, v[48:49] offset:256
	flat_load_dword v95, v[48:49] offset:384
	v_and_b32_e32 v48, 1, v202
	v_cmp_eq_u32_e64 s[10:11], 0, v48
	v_lshl_add_u64 v[48:49], s[12:13], 0, v[196:197]
	s_waitcnt lgkmcnt(0)
	v_pk_add_f32 v[16:17], v[16:17], v[32:33]
	ds_bpermute_b32 v33, v121, v17
	ds_bpermute_b32 v32, v121, v16
	v_lshlrev_b32_e32 v196, 14, v203
	v_lshl_add_u64 v[48:49], v[48:49], 0, v[196:197]
	s_waitcnt vmcnt(0)
	v_mul_f32_e32 v64, v64, v120
	s_nop 1
	v_mov_b32_dpp v65, v64 quad_perm:[1,0,3,2] row_mask:0xf bank_mask:0xf
	s_and_saveexec_b64 s[12:13], s[10:11]
	s_cbranch_execz .LBB0_826
	s_waitcnt lgkmcnt(0)
	v_cvt_pk_bf16_f32 v64, v64, v65
	global_store_dword v[48:49], v64, off

; __device__ __forceinline__ int crow(int r, int hi) { return (r & 3) + 8 * (r >> 2) + 4 * hi; }
; __device__ __forceinline__ bool fox_block(const BlockRef& cur, BlockRef& nxt, unsigned* ctr, const unsigned* nrm, bf16_t* PROJ, bf16_t* MIX, char* lds, Seam& S, const float* __restrict__ CF, const float* __restrict__ fnorm) {
;     ...
;     if (hi == 0) li_l[r32] = l_reg; asm volatile("s_waitcnt lgkmcnt(0)" ::: "memory");
;     float rs[16];
; #pragma unroll
;     for (int r = 0; r < 16; ++r) { const float rl = __builtin_amdgcn_rcpf(li_l[crow(r, hi)]); float a = 0.f;
; #pragma unroll
;         for (int d0 = 0; d0 < 4; ++d0) { const float v = o[d0][r] * rl; o[d0][r] = v; a += v * v; }
;         a += __shfl_xor(a, 1); a += __shfl_xor(a, 2); a += __shfl_xor(a, 4); a += __shfl_xor(a, 8); a += __shfl_xor(a, 16);
;         rs[r] = rsqrtf(a * (1.f / 128.f) + RMS_EPS); }
.LBB0_2250:
	s_ashr_i32 s73, s72, 31
	s_waitcnt vmcnt(8)
	s_waitcnt vmcnt(0) lgkmcnt(0)
	ds_write_b128 v213, v[102:105] offset:32768
	ds_write_b128 v213, v[110:113] offset:40960
	v_cmp_gt_u32_e32 vcc, 32, v214
	s_and_saveexec_b64 s[10:11], vcc
	ds_write_b32 v215, v114
	s_or_b64 exec, exec, s[10:11]
	v_and_b32_e32 v67, 64, v207
	v_xor_b32_e32 v66, 1, v207
	v_add_u32_e32 v67, 64, v67
	v_cmp_lt_i32_e32 vcc, v66, v67
	s_waitcnt lgkmcnt(0)
	v_mov_b32_e32 v74, v50
	v_mov_b32_e32 v75, v34
	v_cndmask_b32_e32 v66, v207, v66, vcc
	v_lshlrev_b32_e32 v116, 2, v66
	v_xor_b32_e32 v66, 2, v207
	v_cmp_lt_i32_e32 vcc, v66, v67
	v_mov_b32_e32 v34, v51
	v_lshl_or_b32 v196, s22, 7, v211
	v_cndmask_b32_e32 v66, v207, v66, vcc
	v_lshlrev_b32_e32 v118, 2, v66
	v_xor_b32_e32 v66, 4, v207
	v_cmp_lt_i32_e32 vcc, v66, v67
	s_nop 1
	v_cndmask_b32_e32 v66, v207, v66, vcc
	v_lshlrev_b32_e32 v119, 2, v66
	v_xor_b32_e32 v66, 8, v207
	v_cmp_lt_i32_e32 vcc, v66, v67
	s_nop 1
	v_cndmask_b32_e32 v66, v207, v66, vcc
	v_lshlrev_b32_e32 v120, 2, v66
	v_xor_b32_e32 v66, 16, v207
	v_cmp_lt_i32_e32 vcc, v66, v67
	s_nop 1
	v_cndmask_b32_e32 v66, v207, v66, vcc
	v_lshlrev_b32_e32 v121, 2, v66
	ds_read_b128 v[70:73], v212
	ds_read_b128 v[66:69], v212 offset:32
	s_waitcnt lgkmcnt(0)
	v_rcp_f32_e32 v70, v70
	s_nop 0
	v_pk_mul_f32 v[86:87], v[74:75], v[70:71] op_sel_hi:[1,0]
	v_mov_b32_e32 v74, v2
	v_rcp_f32_e32 v2, v71
	v_mov_b32_e32 v75, v18
	v_mov_b32_e32 v18, v3
	v_pk_mul_f32 v[76:77], v[86:87], v[86:87]
	v_pk_mul_f32 v[80:81], v[34:35], v[2:3] op_sel_hi:[1,0]
	v_pk_mul_f32 v[84:85], v[74:75], v[70:71] op_sel_hi:[1,0]
	v_pk_mul_f32 v[34:35], v[80:81], v[80:81]
	v_pk_mul_f32 v[74:75], v[18:19], v[2:3] op_sel_hi:[1,0]
	v_pk_mul_f32 v[78:79], v[84:85], v[84:85]
	v_pk_mul_f32 v[2:3], v[74:75], v[74:75]
	v_mov_b32_e32 v18, v34
	v_mov_b32_e32 v19, v76
	v_mov_b32_e32 v76, v35
	v_pk_add_f32 v[18:19], v[18:19], v[76:77]
	v_mov_b32_e32 v34, v3
	v_mov_b32_e32 v35, v79
	v_pk_add_f32 v[18:19], v[34:35], v[18:19]
	v_mov_b32_e32 v3, v78
	v_pk_add_f32 v[2:3], v[2:3], v[18:19]
	s_nop 1
	v_mov_b32_dpp v19, v3 quad_perm:[1,0,3,2] row_mask:0xf bank_mask:0xf
	s_nop 1
	v_mov_b32_dpp v18, v2 quad_perm:[1,0,3,2] row_mask:0xf bank_mask:0xf
	v_mov_b32_e32 v34, v4
	v_rcp_f32_e32 v4, v73
	v_mov_b32_e32 v35, v20
	v_mov_b32_e32 v20, v5
	s_waitcnt lgkmcnt(0)
	v_pk_add_f32 v[2:3], v[2:3], v[18:19]
	s_nop 1
	v_mov_b32_dpp v19, v3 quad_perm:[2,3,0,1] row_mask:0xf bank_mask:0xf
	s_nop 1
	v_mov_b32_dpp v18, v2 quad_perm:[2,3,0,1] row_mask:0xf bank_mask:0xf
	s_waitcnt lgkmcnt(0)
	v_pk_add_f32 v[2:3], v[2:3], v[18:19]
	ds_bpermute_b32 v19, v119, v3
	ds_bpermute_b32 v18, v119, v2
	s_waitcnt lgkmcnt(0)
	v_pk_add_f32 v[2:3], v[2:3], v[18:19]
	ds_bpermute_b32 v19, v120, v3
	ds_bpermute_b32 v18, v120, v2
	s_waitcnt lgkmcnt(0)
	v_pk_add_f32 v[2:3], v[2:3], v[18:19]
	ds_bpermute_b32 v19, v121, v3
	ds_bpermute_b32 v18, v121, v2
	s_waitcnt lgkmcnt(0)
	v_pk_add_f32 v[2:3], v[2:3], v[18:19]
	s_nop 0
	v_pk_fma_f32 v[94:95], v[2:3], s[48:49], v[198:199] op_sel_hi:[1,0,0]
	v_mov_b32_e32 v18, v52
	v_mul_f32_e32 v2, 0x4b800000, v95
	v_cmp_gt_f32_e64 s[10:11], s44, v95
	v_mov_b32_e32 v19, v36
	v_mov_b32_e32 v36, v53
	v_cndmask_b32_e64 v2, v95, v2, s[10:11]
	v_rsq_f32_e32 v2, v2
	v_pk_mul_f32 v[78:79], v[36:37], v[4:5] op_sel_hi:[1,0]
	v_cmp_gt_f32_e32 vcc, s44, v94
	v_mul_f32_e32 v3, 0x45800000, v2
	v_cndmask_b32_e64 v117, v2, v3, s[10:11]
	v_rcp_f32_e32 v2, v72
	v_pk_mul_f32 v[72:73], v[20:21], v[4:5] op_sel_hi:[1,0]
	s_lshl_b64 s[10:11], s[72:73], 12
	v_pk_mul_f32 v[4:5], v[72:73], v[72:73]
	v_pk_mul_f32 v[88:89], v[18:19], v[2:3] op_sel_hi:[1,0]
	v_pk_mul_f32 v[82:83], v[34:35], v[2:3] op_sel_hi:[1,0]
	v_pk_mul_f32 v[18:19], v[88:89], v[88:89]
	v_pk_mul_f32 v[34:35], v[78:79], v[78:79]
	v_pk_mul_f32 v[2:3], v[82:83], v[82:83]
	v_mov_b32_e32 v20, v34
	v_mov_b32_e32 v21, v18
	v_mov_b32_e32 v18, v35
	v_pk_add_f32 v[18:19], v[20:21], v[18:19]
	v_mov_b32_e32 v20, v5
	v_mov_b32_e32 v21, v3
	v_pk_add_f32 v[18:19], v[20:21], v[18:19]
	v_mov_b32_e32 v5, v2
	v_pk_add_f32 v[2:3], v[4:5], v[18:19]
	s_nop 1
	v_mov_b32_dpp v5, v3 quad_perm:[1,0,3,2] row_mask:0xf bank_mask:0xf
	s_nop 1
	v_mov_b32_dpp v4, v2 quad_perm:[1,0,3,2] row_mask:0xf bank_mask:0xf
	v_mov_b32_e32 v18, v6
	v_rcp_f32_e32 v6, v67
	v_mov_b32_e32 v19, v22
	v_mov_b32_e32 v22, v7
	s_waitcnt lgkmcnt(0)
	v_pk_add_f32 v[2:3], v[2:3], v[4:5]
	s_nop 1
	v_mov_b32_dpp v5, v3 quad_perm:[2,3,0,1] row_mask:0xf bank_mask:0xf
	s_nop 1
	v_mov_b32_dpp v4, v2 quad_perm:[2,3,0,1] row_mask:0xf bank_mask:0xf
	v_pk_mul_f32 v[50:51], v[22:23], v[6:7] op_sel_hi:[1,0]
	s_add_u32 s12, s70, s10
	s_addc_u32 s13, s71, s11
	s_waitcnt lgkmcnt(0)
	v_pk_add_f32 v[2:3], v[2:3], v[4:5]
	ds_bpermute_b32 v5, v119, v3
	ds_bpermute_b32 v4, v119, v2
	s_waitcnt lgkmcnt(0)
	v_pk_add_f32 v[2:3], v[2:3], v[4:5]
	ds_bpermute_b32 v5, v120, v3
	ds_bpermute_b32 v4, v120, v2
	s_waitcnt lgkmcnt(0)
	v_pk_add_f32 v[96:97], v[2:3], v[4:5]
	v_rcp_f32_e32 v2, v66
	v_mov_b32_e32 v4, v54
	v_mov_b32_e32 v5, v38
	v_mov_b32_e32 v38, v55
	v_pk_mul_f32 v[76:77], v[4:5], v[2:3] op_sel_hi:[1,0]
	v_pk_mul_f32 v[54:55], v[38:39], v[6:7] op_sel_hi:[1,0]
	v_pk_mul_f32 v[4:5], v[76:77], v[76:77]
	v_pk_mul_f32 v[70:71], v[18:19], v[2:3] op_sel_hi:[1,0]
	v_pk_mul_f32 v[18:19], v[54:55], v[54:55]
	v_pk_mul_f32 v[2:3], v[70:71], v[70:71]
	v_pk_mul_f32 v[6:7], v[50:51], v[50:51]
	v_mov_b32_e32 v20, v18
	v_mov_b32_e32 v21, v4
	v_mov_b32_e32 v4, v19
	v_pk_add_f32 v[4:5], v[20:21], v[4:5]
	v_mov_b32_e32 v18, v7
	v_mov_b32_e32 v19, v3
	v_pk_add_f32 v[4:5], v[18:19], v[4:5]
	v_mov_b32_e32 v7, v2
	v_pk_add_f32 v[2:3], v[6:7], v[4:5]
	s_nop 1
	v_mov_b32_dpp v5, v3 quad_perm:[1,0,3,2] row_mask:0xf bank_mask:0xf
	s_nop 1
	v_mov_b32_dpp v4, v2 quad_perm:[1,0,3,2] row_mask:0xf bank_mask:0xf
	v_mov_b32_e32 v6, v8
	v_mov_b32_e32 v7, v24
	v_mov_b32_e32 v24, v9
	ds_bpermute_b32 v115, v121, v97
	s_waitcnt lgkmcnt(0)
; __device__ __forceinline__ int crow(int r, int hi) { return (r & 3) + 8 * (r >> 2) + 4 * hi; }
; __device__ __forceinline__ bool fox_block(const BlockRef& cur, BlockRef& nxt, unsigned* ctr, const unsigned* nrm, bf16_t* PROJ, bf16_t* MIX, char* lds, Seam& S, const float* __restrict__ CF, const float* __restrict__ fnorm) {
;     ...
;     for (int r = 0; r < 16; ++r) { const float rl = __builtin_amdgcn_rcpf(li_l[crow(r, hi)]); float a = 0.f;
; #pragma unroll
;         for (int d0 = 0; d0 < 4; ++d0) { const float v = o[d0][r] * rl; o[d0][r] = v; a += v * v; }
;         a += __shfl_xor(a, 1); a += __shfl_xor(a, 2); a += __shfl_xor(a, 4); a += __shfl_xor(a, 8); a += __shfl_xor(a, 16);
;         rs[r] = rsqrtf(a * (1.f / 128.f) + RMS_EPS); }
	v_pk_add_f32 v[2:3], v[2:3], v[4:5]
	s_nop 1
	v_mov_b32_dpp v5, v3 quad_perm:[2,3,0,1] row_mask:0xf bank_mask:0xf
	s_nop 1
	v_mov_b32_dpp v4, v2 quad_perm:[2,3,0,1] row_mask:0xf bank_mask:0xf
	ds_bpermute_b32 v114, v121, v96
	s_waitcnt lgkmcnt(0)
	v_pk_add_f32 v[2:3], v[2:3], v[4:5]
	ds_bpermute_b32 v5, v119, v3
	ds_bpermute_b32 v4, v119, v2
	s_waitcnt lgkmcnt(0)
	v_pk_add_f32 v[2:3], v[2:3], v[4:5]
	ds_bpermute_b32 v5, v120, v3
	ds_bpermute_b32 v4, v120, v2
	s_waitcnt lgkmcnt(0)
	v_pk_add_f32 v[90:91], v[2:3], v[4:5]
	v_rcp_f32_e32 v2, v68
	v_mov_b32_e32 v4, v56
	v_mov_b32_e32 v5, v40
	v_mov_b32_e32 v40, v57
	v_pk_mul_f32 v[52:53], v[6:7], v[2:3] op_sel_hi:[1,0]
	v_rcp_f32_e32 v6, v69
	v_pk_mul_f32 v[66:67], v[4:5], v[2:3] op_sel_hi:[1,0]
	v_pk_mul_f32 v[2:3], v[52:53], v[52:53]
	v_pk_mul_f32 v[4:5], v[66:67], v[66:67]
	v_pk_mul_f32 v[40:41], v[40:41], v[6:7] op_sel_hi:[1,0]
	v_pk_mul_f32 v[36:37], v[24:25], v[6:7] op_sel_hi:[1,0]
	v_pk_mul_f32 v[18:19], v[40:41], v[40:41]
	v_pk_mul_f32 v[6:7], v[36:37], v[36:37]
	v_mov_b32_e32 v8, v18
	v_mov_b32_e32 v9, v4
	v_mov_b32_e32 v4, v19
	v_pk_add_f32 v[4:5], v[8:9], v[4:5]
	v_mov_b32_e32 v8, v7
	v_mov_b32_e32 v9, v3
	v_pk_add_f32 v[4:5], v[8:9], v[4:5]
	v_mov_b32_e32 v7, v2
	v_pk_add_f32 v[2:3], v[6:7], v[4:5]
	s_nop 1
	v_mov_b32_dpp v5, v3 quad_perm:[1,0,3,2] row_mask:0xf bank_mask:0xf
	s_nop 1
	v_mov_b32_dpp v4, v2 quad_perm:[1,0,3,2] row_mask:0xf bank_mask:0xf
	v_mov_b32_e32 v6, v58
	v_mov_b32_e32 v7, v42
	v_mov_b32_e32 v8, v10
	v_mov_b32_e32 v9, v26
	s_waitcnt lgkmcnt(0)
	v_pk_add_f32 v[2:3], v[2:3], v[4:5]
	s_nop 1
	v_mov_b32_dpp v5, v3 quad_perm:[2,3,0,1] row_mask:0xf bank_mask:0xf
	s_nop 1
	v_mov_b32_dpp v4, v2 quad_perm:[2,3,0,1] row_mask:0xf bank_mask:0xf
	v_mov_b32_e32 v42, v59
	v_mov_b32_e32 v26, v11
	ds_bpermute_b32 v93, v121, v91
	ds_bpermute_b32 v92, v121, v90
	s_waitcnt lgkmcnt(0)
	v_pk_add_f32 v[2:3], v[2:3], v[4:5]
	ds_bpermute_b32 v5, v119, v3
	ds_bpermute_b32 v4, v119, v2
	s_waitcnt lgkmcnt(0)
	v_pk_add_f32 v[2:3], v[2:3], v[4:5]
	ds_bpermute_b32 v5, v120, v3
	ds_bpermute_b32 v4, v120, v2
	s_waitcnt lgkmcnt(0)
	v_pk_add_f32 v[56:57], v[2:3], v[4:5]
	ds_read_b128 v[2:5], v212 offset:64
	ds_bpermute_b32 v69, v121, v57
	ds_bpermute_b32 v68, v121, v56
	s_waitcnt lgkmcnt(0)
	v_rcp_f32_e32 v2, v2
	s_nop 0
	v_pk_mul_f32 v[38:39], v[6:7], v[2:3] op_sel_hi:[1,0]
	v_pk_mul_f32 v[34:35], v[8:9], v[2:3] op_sel_hi:[1,0]
	v_rcp_f32_e32 v2, v3
	v_pk_mul_f32 v[6:7], v[38:39], v[38:39]
	v_pk_mul_f32 v[8:9], v[34:35], v[34:35]
	v_mov_b32_e32 v11, v6
	v_pk_mul_f32 v[24:25], v[42:43], v[2:3] op_sel_hi:[1,0]
	v_pk_mul_f32 v[20:21], v[26:27], v[2:3] op_sel_hi:[1,0]
	v_pk_mul_f32 v[18:19], v[24:25], v[24:25]
	v_pk_mul_f32 v[2:3], v[20:21], v[20:21]
	v_mov_b32_e32 v10, v18
	v_mov_b32_e32 v6, v19
	v_pk_add_f32 v[6:7], v[10:11], v[6:7]
	v_mov_b32_e32 v10, v3
	v_mov_b32_e32 v11, v9
	v_pk_add_f32 v[6:7], v[10:11], v[6:7]
	v_mov_b32_e32 v3, v8
	v_pk_add_f32 v[2:3], v[2:3], v[6:7]
	s_nop 1
	v_mov_b32_dpp v7, v3 quad_perm:[1,0,3,2] row_mask:0xf bank_mask:0xf
	s_nop 1
	v_mov_b32_dpp v6, v2 quad_perm:[1,0,3,2] row_mask:0xf bank_mask:0xf
	s_waitcnt lgkmcnt(0)
	v_pk_add_f32 v[2:3], v[2:3], v[6:7]
	s_nop 1
	v_mov_b32_dpp v7, v3 quad_perm:[2,3,0,1] row_mask:0xf bank_mask:0xf
	s_nop 1
	v_mov_b32_dpp v6, v2 quad_perm:[2,3,0,1] row_mask:0xf bank_mask:0xf
	s_waitcnt lgkmcnt(0)
	v_pk_add_f32 v[2:3], v[2:3], v[6:7]
	ds_bpermute_b32 v7, v119, v3
	ds_bpermute_b32 v6, v119, v2
	s_waitcnt lgkmcnt(0)
	v_pk_add_f32 v[2:3], v[2:3], v[6:7]
	ds_bpermute_b32 v7, v120, v3
	ds_bpermute_b32 v6, v120, v2
	s_waitcnt lgkmcnt(0)
	v_pk_add_f32 v[26:27], v[2:3], v[6:7]
	v_rcp_f32_e32 v2, v4
	v_rcp_f32_e32 v4, v5
	v_mov_b32_e32 v6, v60
	v_mov_b32_e32 v7, v44
	v_mov_b32_e32 v44, v61
	v_pk_mul_f32 v[18:19], v[6:7], v[2:3] op_sel_hi:[1,0]
	v_mov_b32_e32 v6, v12
	v_mov_b32_e32 v7, v28
	v_pk_mul_f32 v[8:9], v[44:45], v[4:5] op_sel_hi:[1,0]
	v_mov_b32_e32 v28, v13
	v_pk_mul_f32 v[22:23], v[18:19], v[18:19]
	v_pk_mul_f32 v[10:11], v[6:7], v[2:3] op_sel_hi:[1,0]
	v_pk_mul_f32 v[44:45], v[8:9], v[8:9]
	v_pk_mul_f32 v[6:7], v[28:29], v[4:5] op_sel_hi:[1,0]
	v_pk_mul_f32 v[2:3], v[10:11], v[10:11]
	v_pk_mul_f32 v[4:5], v[6:7], v[6:7]
	v_mov_b32_e32 v12, v44
	v_mov_b32_e32 v13, v22
	v_mov_b32_e32 v22, v45
	v_pk_add_f32 v[12:13], v[12:13], v[22:23]
	v_mov_b32_e32 v22, v5
	v_mov_b32_e32 v23, v3
	v_pk_add_f32 v[12:13], v[22:23], v[12:13]
	v_mov_b32_e32 v5, v2
	v_pk_add_f32 v[2:3], v[4:5], v[12:13]
	s_nop 1
	v_mov_b32_dpp v5, v3 quad_perm:[1,0,3,2] row_mask:0xf bank_mask:0xf
	s_nop 1
	v_mov_b32_dpp v4, v2 quad_perm:[1,0,3,2] row_mask:0xf bank_mask:0xf
	v_mov_b32_e32 v28, v62
	v_mov_b32_e32 v29, v46
	v_mov_b32_e32 v44, v14
	v_mov_b32_e32 v45, v30
	s_waitcnt lgkmcnt(0)
; __device__ __forceinline__ unsigned cvt_pk_bf16(float lo, float hi) { unsigned r; asm volatile("v_cvt_pk_bf16_f32 %0, %1, %2" : "=v"(r) : "v"(lo), "v"(hi)); return r; }
; __device__ __forceinline__ int crow(int r, int hi) { return (r & 3) + 8 * (r >> 2) + 4 * hi; }
; __device__ __forceinline__ bool fox_block(const BlockRef& cur, BlockRef& nxt, unsigned* ctr, const unsigned* nrm, bf16_t* PROJ, bf16_t* MIX, char* lds, Seam& S, const float* __restrict__ CF, const float* __restrict__ fnorm) {
;     ...
;     for (int r = 0; r < 16; ++r) { const float rl = __builtin_amdgcn_rcpf(li_l[crow(r, hi)]); float a = 0.f;
; #pragma unroll
;         for (int d0 = 0; d0 < 4; ++d0) { const float v = o[d0][r] * rl; o[d0][r] = v; a += v * v; }
;         a += __shfl_xor(a, 1); a += __shfl_xor(a, 2); a += __shfl_xor(a, 4); a += __shfl_xor(a, 8); a += __shfl_xor(a, 16);
;         rs[r] = rsqrtf(a * (1.f / 128.f) + RMS_EPS); }
;     float gn[4];
; #pragma unroll
;     for (int d0 = 0; d0 < 4; ++d0) gn[d0] = fnorm[cur.head * 128 + d0 * 32 + r32];
;     bf16_t* Ow = cur.O + (size_t)(wid * QBLK) * DM;
; #pragma unroll
;     for (int r = 0; r < 16; ++r) { const int orow = crow(r, hi);
; #pragma unroll
;         for (int d0 = 0; d0 < 4; ++d0) { const float v = o[d0][r] * rs[r] * gn[d0];
;             const float vn = __shfl_xor(v, 1);
;             if ((r32 & 1) == 0) *(unsigned*)(Ow + (size_t)orow * DM + d0 * 32 + r32) = cvt_pk_bf16(v, vn); } }
	v_pk_add_f32 v[2:3], v[2:3], v[4:5]
	s_nop 1
	v_mov_b32_dpp v5, v3 quad_perm:[2,3,0,1] row_mask:0xf bank_mask:0xf
	s_nop 1
	v_mov_b32_dpp v4, v2 quad_perm:[2,3,0,1] row_mask:0xf bank_mask:0xf
	v_mov_b32_e32 v46, v63
	v_mov_b32_e32 v30, v15
	ds_bpermute_b32 v43, v121, v27
	ds_bpermute_b32 v42, v121, v26
	s_waitcnt lgkmcnt(0)
	v_pk_add_f32 v[2:3], v[2:3], v[4:5]
	ds_bpermute_b32 v5, v119, v3
	ds_bpermute_b32 v4, v119, v2
	s_waitcnt lgkmcnt(0)
	v_pk_add_f32 v[2:3], v[2:3], v[4:5]
	ds_bpermute_b32 v5, v120, v3
	ds_bpermute_b32 v4, v120, v2
	s_waitcnt lgkmcnt(0)
	v_pk_add_f32 v[12:13], v[2:3], v[4:5]
	ds_read_b128 v[2:5], v212 offset:96
	ds_bpermute_b32 v23, v121, v13
	ds_bpermute_b32 v22, v121, v12
	s_waitcnt lgkmcnt(0)
	v_rcp_f32_e32 v2, v2
	s_nop 0
	v_pk_mul_f32 v[60:61], v[28:29], v[2:3] op_sel_hi:[1,0]
	v_pk_mul_f32 v[58:59], v[44:45], v[2:3] op_sel_hi:[1,0]
	v_rcp_f32_e32 v2, v3
	v_pk_mul_f32 v[28:29], v[60:61], v[60:61]
	v_pk_mul_f32 v[122:123], v[58:59], v[58:59]
	v_mov_b32_e32 v15, v28
	v_pk_mul_f32 v[44:45], v[46:47], v[2:3] op_sel_hi:[1,0]
	v_pk_mul_f32 v[30:31], v[30:31], v[2:3] op_sel_hi:[1,0]
	v_pk_mul_f32 v[46:47], v[44:45], v[44:45]
	v_pk_mul_f32 v[2:3], v[30:31], v[30:31]
	v_mov_b32_e32 v14, v46
	v_mov_b32_e32 v28, v47
	v_pk_add_f32 v[14:15], v[14:15], v[28:29]
	v_mov_b32_e32 v28, v3
	v_mov_b32_e32 v29, v123
	v_pk_add_f32 v[14:15], v[28:29], v[14:15]
	v_mov_b32_e32 v3, v122
	v_pk_add_f32 v[2:3], v[2:3], v[14:15]
	s_nop 1
	v_mov_b32_dpp v15, v3 quad_perm:[1,0,3,2] row_mask:0xf bank_mask:0xf
	s_nop 1
	v_mov_b32_dpp v14, v2 quad_perm:[1,0,3,2] row_mask:0xf bank_mask:0xf
	s_waitcnt lgkmcnt(0)
	v_pk_add_f32 v[2:3], v[2:3], v[14:15]
	s_nop 1
	v_mov_b32_dpp v15, v3 quad_perm:[2,3,0,1] row_mask:0xf bank_mask:0xf
	s_nop 1
	v_mov_b32_dpp v14, v2 quad_perm:[2,3,0,1] row_mask:0xf bank_mask:0xf
	s_waitcnt lgkmcnt(0)
	v_pk_add_f32 v[2:3], v[2:3], v[14:15]
	ds_bpermute_b32 v15, v119, v3
	ds_bpermute_b32 v14, v119, v2
	s_waitcnt lgkmcnt(0)
	v_pk_add_f32 v[2:3], v[2:3], v[14:15]
	ds_bpermute_b32 v15, v120, v3
	ds_bpermute_b32 v14, v120, v2
	s_waitcnt lgkmcnt(0)
	v_pk_add_f32 v[46:47], v[2:3], v[14:15]
	v_rcp_f32_e32 v2, v4
	v_mov_b32_e32 v14, v64
	v_mov_b32_e32 v15, v48
	v_mov_b32_e32 v48, v65
	v_pk_mul_f32 v[28:29], v[14:15], v[2:3] op_sel_hi:[1,0]
	v_mov_b32_e32 v14, v16
	v_mov_b32_e32 v15, v32
	v_pk_mul_f32 v[14:15], v[14:15], v[2:3] op_sel_hi:[1,0]
	v_rcp_f32_e32 v2, v5
	v_mov_b32_e32 v32, v17
	v_pk_mul_f32 v[122:123], v[28:29], v[28:29]
	v_pk_mul_f32 v[124:125], v[14:15], v[14:15]
	v_pk_mul_f32 v[4:5], v[48:49], v[2:3] op_sel_hi:[1,0]
	v_pk_mul_f32 v[2:3], v[32:33], v[2:3] op_sel_hi:[1,0]
	v_pk_mul_f32 v[48:49], v[4:5], v[4:5]
	v_pk_mul_f32 v[16:17], v[2:3], v[2:3]
	v_mov_b32_e32 v32, v48
	v_mov_b32_e32 v33, v122
	v_mov_b32_e32 v122, v49
	v_pk_add_f32 v[32:33], v[32:33], v[122:123]
	v_mov_b32_e32 v48, v17
	v_mov_b32_e32 v49, v125
	v_pk_add_f32 v[32:33], v[48:49], v[32:33]
	v_mov_b32_e32 v17, v124
	v_pk_add_f32 v[16:17], v[16:17], v[32:33]
	s_nop 1
	v_mov_b32_dpp v33, v17 quad_perm:[1,0,3,2] row_mask:0xf bank_mask:0xf
	s_nop 1
	v_mov_b32_dpp v32, v16 quad_perm:[1,0,3,2] row_mask:0xf bank_mask:0xf
	v_lshl_add_u64 v[48:49], v[196:197], 2, s[60:61]
	v_mul_f32_e32 v64, v86, v117
	ds_bpermute_b32 v63, v121, v47
	ds_bpermute_b32 v62, v121, v46
	s_waitcnt lgkmcnt(0)
	v_pk_add_f32 v[16:17], v[16:17], v[32:33]
	s_nop 1
	v_mov_b32_dpp v33, v17 quad_perm:[2,3,0,1] row_mask:0xf bank_mask:0xf
	s_nop 1
	v_mov_b32_dpp v32, v16 quad_perm:[2,3,0,1] row_mask:0xf bank_mask:0xf
	v_lshlrev_b32_e32 v196, 1, v211
	s_waitcnt lgkmcnt(0)
	v_pk_add_f32 v[16:17], v[16:17], v[32:33]
	ds_bpermute_b32 v33, v119, v17
	ds_bpermute_b32 v32, v119, v16
	s_waitcnt lgkmcnt(0)
	v_pk_add_f32 v[16:17], v[16:17], v[32:33]
	ds_bpermute_b32 v33, v120, v17
	ds_bpermute_b32 v32, v120, v16
	flat_load_dword v120, v[48:49]
	flat_load_dword v119, v[48:49] offset:128
	flat_load_dword v118, v[48:49] offset:256
	flat_load_dword v95, v[48:49] offset:384
	v_and_b32_e32 v48, 1, v202
	v_cmp_eq_u32_e64 s[10:11], 0, v48
	v_lshl_add_u64 v[48:49], s[12:13], 0, v[196:197]
	s_waitcnt lgkmcnt(0)
	v_pk_add_f32 v[16:17], v[16:17], v[32:33]
	ds_bpermute_b32 v33, v121, v17
	ds_bpermute_b32 v32, v121, v16
	v_lshlrev_b32_e32 v196, 14, v203
	v_lshl_add_u64 v[48:49], v[48:49], 0, v[196:197]
	s_waitcnt vmcnt(0)
	v_mul_f32_e32 v64, v64, v120
	s_nop 1
	v_mov_b32_dpp v65, v64 quad_perm:[1,0,3,2] row_mask:0xf bank_mask:0xf
	s_and_saveexec_b64 s[12:13], s[10:11]
	s_cbranch_execz .LBB0_2254
	s_waitcnt lgkmcnt(0)
	v_cvt_pk_bf16_f32 v64, v64, v65
	global_store_dword v[48:49], v64, off
